# rope tables spread over 3 workgroups (on top of adaLN load hoist)
# speedup vs baseline: 1.0228x; 1.0042x over previous
; __global__ void __launch_bounds__(512, 2) mk_fwd(Args args) {
;     ...
;     if (threadIdx.x == 0) { ((volatile LAS unsigned*)(lds + LDS_BARST))[0] = 0u; ((volatile LAS unsigned*)(lds + LDS_BARST))[1] = 0u; }
;     __syncthreads();
;     const XcdBarrier xbar = xcd_barrier_post((unsigned*)args.ws, (volatile LAS unsigned*)(lds + LDS_BARST));
;     for (int ph = args.ph_lo; ph < args.ph_hi; ++ph) {
;         unsigned char* ws = args.ws; asm volatile("" : "+s"(ws));
;         float* MODS = (float*)(ws + WS_MODS);
;         float* tabM = (float*)(ws + WS_TAB); float* tabS = tabM + 1024;
;         float* XC = (float*)(ws + WS_XC); float* XL = args.out;
;         bf16_t* WB = (bf16_t*)(ws + WS_W);
;         bf16_t* HO = (bf16_t*)(ws + WS_HO);
;         bf16_t* Z = (bf16_t*)(ws + WS_Z);
;         bf16_t* Q2 = (bf16_t*)(ws + WS_Q2);
;         bf16_t* KV2 = (bf16_t*)(ws + WS_KV2);
;         bf16_t* GB = (bf16_t*)(ws + WS_G);
;         float* HALO = (float*)(ws + WS_HALO);
;         float* STAT = (float*)(ws + WS_STAT);
;         float* SSQ = (float*)(ws + WS_SSQ);
;         int l = 0, kind = 100 + ph;
;         if (ph >= 2) {
;             const unsigned long long SEQ_E = 0x0ull | (1ull << 4) | (2ull << 8) | (3ull << 12) | (4ull << 16) | (9ull << 20) | (5ull << 24) | (6ull << 28) | (7ull << 32) | (8ull << 36) | (10ull << 40);
;             const unsigned long long SEQ_O = 0x0ull | (2ull << 4) | (3ull << 8) | (4ull << 12) | (9ull << 16) | (5ull << 20) | (6ull << 24) | (7ull << 28) | (8ull << 32) | (10ull << 36);
;             const unsigned long long SEQ_L = 0x0ull | (2ull << 4) | (3ull << 8) | (4ull << 12) | (5ull << 16) | (6ull << 20) | (7ull << 24) | (8ull << 28);
;             unsigned long long seq; int pos;
;             if (ph < 13) { l = 0; seq = SEQ_E; pos = ph - 2; } else if (ph < 23) { l = 1; seq = SEQ_O; pos = ph - 13; } else if (ph < 34) { l = 2; seq = SEQ_E; pos = ph - 23; } else { l = 3; seq = SEQ_L; pos = ph - 34; }
;             kind = (int)((seq >> (4 * pos)) & 15ull);
;         }
;         int cv_lo = 0, cv_hi = 0, cv_w = 0, cv_n = 1;
;         if (ph == 0 && EN(100)) {
;             GET_TID();
;             for (int it = blockIdx.x; it < 768; it += G) {
;                 const int l = it / 192, col0 = (it % 192) * 32, d0 = wid * 128;
;                 LAS float* sc = (LAS float*)(lds + wid * 10240);
;                 for (int b = 0; b < 17; ++b)
.LBB0_5:
	s_or_b64 exec, exec, s[4:5]
	s_cmp_ge_i32 s60, s61
	s_cbranch_scc1 .LBB0_863
	s_and_b32 s4, s21, 7
	s_ashr_i32 s5, s62, 3
	s_mul_i32 s4, s5, s4
	s_lshr_b32 s5, s21, 3
	s_ashr_i32 s23, s21, 31
	s_add_i32 s4, s4, s5
	s_lshr_b32 s5, s23, 29
	s_add_i32 s5, s21, s5
	s_ashr_i32 s6, s5, 3
	s_and_b32 s5, s5, -8
	s_lshl_b32 s24, s62, 3
	s_and_b32 s3, s62, 7
	v_writelane_b32 v252, s6, 20
	s_sub_i32 s6, s21, s5
	s_ashr_i32 s22, s62, 31
	s_and_b32 s5, s21, 3
	s_cmp_eq_u32 s5, 0
	s_cselect_b64 s[8:9], -1, 0
	v_writelane_b32 v252, s8, 21
	s_lshl_b32 s5, s21, 3
	s_load_dwordx16 s[36:51], s[0:1], 0x80
	v_writelane_b32 v252, s9, 22
	v_writelane_b32 v252, s5, 23
	s_lshr_b32 s5, s21, 2
	v_writelane_b32 v252, s5, 24
	s_not_b32 s5, s5
	v_writelane_b32 v252, s5, 25
	s_lshr_b32 s5, s22, 30
	s_add_i32 s5, s62, s5
	s_ashr_i32 s5, s5, 2
	v_writelane_b32 v252, s5, 26
	s_sub_i32 s5, s62, s5
	s_lshl_b32 s5, s5, 3
	s_cmpk_lt_i32 s21, 0x300
	v_writelane_b32 v252, s5, 27
	s_cselect_b64 s[8:9], -1, 0
	s_add_i32 s5, s62, -3
	v_writelane_b32 v252, s8, 28
	s_cmp_ge_u32 s21, s5
	v_lshrrev_b32_e32 v1, 20, v0
	v_writelane_b32 v252, s9, 29
	s_cselect_b64 s[8:9], -1, 0
	v_writelane_b32 v252, s8, 30
	v_lshrrev_b32_e32 v0, 10, v0
	v_or_b32_e32 v0, v0, v1
	v_writelane_b32 v252, s9, 31
	s_waitcnt lgkmcnt(0)
	s_add_u32 s8, s50, 0x200
	s_addc_u32 s9, s51, 0
	v_writelane_b32 v252, s8, 32
	s_movk_i32 s83, 0x3ff
	v_and_or_b32 v0, v0, s83, v236
	v_writelane_b32 v252, s9, 33
	s_add_u32 s8, s50, 0x1000
	s_addc_u32 s9, s51, 0
	v_writelane_b32 v252, s8, 34
	s_mov_b32 s80, 0x54442d18
	v_writelane_b32 v254, s21, 0
	v_writelane_b32 v252, s9, 35
	s_add_u32 s8, s50, 0x1100
	s_addc_u32 s9, s51, 0
	v_writelane_b32 v252, s8, 36
	v_mbcnt_lo_u32_b32 v2, -1, 0
	v_mov_b32_e32 v1, 0
	v_writelane_b32 v252, s9, 37
	s_add_u32 s8, s50, 0x1200
	s_addc_u32 s9, s51, 0
	v_writelane_b32 v252, s8, 38
	v_mov_b32_e32 v228, 0x358637bd
	v_mov_b32_e32 v238, 0x260
	v_writelane_b32 v252, s9, 39
	s_add_u32 s8, s50, 0x1300
	s_addc_u32 s9, s51, 0
	v_writelane_b32 v252, s8, 40
	s_cmp_eq_u32 s2, 15
	s_mov_b32 s81, 0x401921fb
	v_writelane_b32 v252, s9, 41
	s_cselect_b64 s[8:9], -1, 0
	v_writelane_b32 v252, s8, 42
	s_cmp_eq_u32 s2, 14
	v_mov_b32_e32 v239, 1
	v_writelane_b32 v252, s9, 43
	s_cselect_b64 s[8:9], -1, 0
	v_writelane_b32 v252, s8, 44
	s_cmp_eq_u32 s2, 13
	v_mov_b32_e32 v229, 0x80
	v_writelane_b32 v252, s9, 45
	s_cselect_b64 s[8:9], -1, 0
	v_writelane_b32 v252, s8, 46
	s_cmp_eq_u32 s2, 12
	v_mov_b32_e32 v241, 0xf149f2ca
	v_writelane_b32 v252, s9, 47
	s_cselect_b64 s[8:9], -1, 0
	v_writelane_b32 v252, s8, 48
	s_cmp_eq_u32 s2, 11
	v_mbcnt_hi_u32_b32 v242, -1, v2
	v_writelane_b32 v252, s9, 49
	s_cselect_b64 s[8:9], -1, 0
	v_writelane_b32 v252, s8, 50
	s_cmp_eq_u32 s2, 10
	v_mov_b32_e32 v230, 0x3b800000
	v_writelane_b32 v252, s9, 51
	s_cselect_b64 s[8:9], -1, 0
	v_writelane_b32 v252, s8, 52
	s_cmp_eq_u32 s2, 9
	v_mov_b32_e32 v244, 0x3b2aaaab
	v_writelane_b32 v252, s9, 53
	s_cselect_b64 s[8:9], -1, 0
	v_writelane_b32 v252, s8, 54
	s_cmp_eq_u32 s2, 8
	v_mov_b32_e32 v245, 0x3e16c740
	v_writelane_b32 v252, s9, 55
	s_cselect_b64 s[8:9], -1, 0
	v_writelane_b32 v252, s8, 56
	s_cmp_eq_u32 s2, 7
	v_mov_b32_e32 v181, 1.0
	v_writelane_b32 v252, s9, 57
	s_cselect_b64 s[8:9], -1, 0
	v_writelane_b32 v252, s8, 58
	s_cmp_eq_u32 s2, 6
	v_mov_b32_e32 v246, 0xb00
	v_writelane_b32 v252, s9, 59
	s_cselect_b64 s[8:9], -1, 0
	v_writelane_b32 v252, s8, 60
	s_cmp_eq_u32 s2, 5
	v_mov_b32_e32 v247, 0x3e38aa3b
	v_writelane_b32 v252, s9, 61
	s_cselect_b64 s[8:9], -1, 0
	v_writelane_b32 v252, s8, 62
	s_cmp_eq_u32 s2, 4
	v_mov_b32_e32 v248, 0x3fe1feb3
	v_writelane_b32 v252, s9, 63
	s_cselect_b64 s[8:9], -1, 0
	v_writelane_b32 v253, s8, 0
	s_cmp_eq_u32 s2, 3
	v_mov_b32_e32 v249, 0x3fd43d13
	v_writelane_b32 v253, s9, 1
	s_cselect_b64 s[8:9], -1, 0
	v_writelane_b32 v253, s8, 2
	s_cmp_eq_u32 s2, 2
	v_mov_b32_e32 v250, 0x3c1c381e
	v_writelane_b32 v253, s9, 3
	s_cselect_b64 s[8:9], -1, 0
	v_writelane_b32 v253, s8, 4
	s_cmp_eq_u32 s2, 1
	v_mov_b32_e32 v251, 0x6248490f
	v_writelane_b32 v253, s9, 5
	s_cselect_b64 s[8:9], -1, 0
	v_writelane_b32 v253, s8, 6
	s_cmp_eq_u32 s2, 0
	s_movk_i32 s90, 0x1200
	v_writelane_b32 v253, s9, 7
	s_cselect_b64 s[8:9], -1, 0
	s_lshl_b32 s2, s2, 8
	s_add_u32 s2, s50, s2
	v_writelane_b32 v253, s8, 8
	s_addc_u32 s5, s51, 0
	s_movk_i32 s33, 0x6000
	v_writelane_b32 v253, s9, 9
	s_add_u32 s8, s2, 0x1400
	s_addc_u32 s9, s5, 0
	v_writelane_b32 v253, s8, 10
	s_movk_i32 s30, 0x50
	s_mov_b32 s28, 0xf800000
	v_writelane_b32 v253, s9, 11
	s_add_u32 s8, s2, 0x2400
	s_addc_u32 s9, s5, 0
	v_writelane_b32 v253, s8, 12
	s_load_dword s2, s[0:1], 0xd0
	s_mov_b32 s29, 0x948000
	v_writelane_b32 v253, s9, 13
	s_add_u32 s8, s50, 0x3400
	s_addc_u32 s9, s51, 0
	v_writelane_b32 v253, s8, 14
	s_waitcnt lgkmcnt(0)
	s_mul_i32 s2, s2, s63
	s_mul_i32 s2, s2, s62
	v_writelane_b32 v253, s9, 15
	s_add_u32 s8, s50, 0x3500
	s_addc_u32 s9, s51, 0
	v_writelane_b32 v253, s8, 16
	s_cmp_eq_u32 s3, 0
	s_mov_b32 s47, 0
	v_writelane_b32 v253, s9, 17
	v_writelane_b32 v253, s2, 18
	s_cselect_b32 s2, s4, s21
	v_writelane_b32 v253, s2, 19
	v_writelane_b32 v253, s6, 20
	s_lshr_b32 s2, s6, 31
	v_writelane_b32 v253, s2, 21
	s_lshl_b32 s2, s21, 11
	v_writelane_b32 v253, s2, 22
	s_lshl_b32 s2, s62, 12
	v_writelane_b32 v253, s2, 23
	s_lshl_b32 s2, s62, 11
	v_writelane_b32 v253, s2, 24
	s_add_i32 s2, 0, 0xa800
	v_writelane_b32 v253, s2, 25
	s_add_i32 s2, 0, 0x22800
	v_writelane_b32 v253, s2, 26
	s_add_i32 s2, 0, 0x22804
	v_writelane_b32 v253, s2, 27
	v_cmp_eq_u32_e64 s[2:3], 0, v0
	s_load_dwordx16 s[4:19], s[0:1], 0x0
	s_ashr_i32 s25, s24, 31
	v_writelane_b32 v253, s2, 28
	s_mov_b64 s[34:35], 0x80
	s_mov_b32 s89, 0xc01921fb
	v_writelane_b32 v253, s3, 29
	s_lshl_b64 s[2:3], s[24:25], 12
	v_writelane_b32 v253, s2, 30
	v_writelane_b32 v254, s24, 1
	s_nop 0
	v_writelane_b32 v253, s3, 31
	s_waitcnt lgkmcnt(0)
	v_writelane_b32 v253, s4, 32
	v_writelane_b32 v254, s25, 2
	v_writelane_b32 v254, s23, 3
	v_writelane_b32 v253, s5, 33
	v_writelane_b32 v253, s6, 34
	v_writelane_b32 v253, s7, 35
	v_writelane_b32 v253, s8, 36
	v_writelane_b32 v253, s9, 37
	v_writelane_b32 v253, s10, 38
	v_writelane_b32 v253, s11, 39
	v_writelane_b32 v253, s12, 40
	v_writelane_b32 v253, s13, 41
	v_writelane_b32 v253, s14, 42
	v_writelane_b32 v253, s15, 43
	v_writelane_b32 v253, s16, 44
	v_writelane_b32 v253, s17, 45
	v_writelane_b32 v253, s18, 46
	v_writelane_b32 v253, s19, 47
	s_load_dwordx16 s[4:19], s[0:1], 0x40
	v_writelane_b32 v254, s22, 4
	s_waitcnt lgkmcnt(0)
	v_writelane_b32 v253, s4, 48
	s_nop 1
	v_writelane_b32 v253, s5, 49
	v_writelane_b32 v253, s6, 50
	v_writelane_b32 v253, s7, 51
	v_writelane_b32 v253, s8, 52
	v_writelane_b32 v253, s9, 53
	v_writelane_b32 v253, s10, 54
	v_writelane_b32 v253, s11, 55
	v_writelane_b32 v253, s12, 56
	v_writelane_b32 v253, s13, 57
	v_writelane_b32 v253, s14, 58
	v_writelane_b32 v253, s15, 59
	v_writelane_b32 v253, s16, 60
	v_writelane_b32 v253, s17, 61
	v_writelane_b32 v253, s18, 62
	v_writelane_b32 v253, s19, 63
	s_branch .LBB0_11

; __global__ void __launch_bounds__(512, 2) mk_fwd(Args args) {
;     ...
;             if (blockIdx.x == G - 1) {
;                 for (int x = tid; x < 64 * 8 + 64 * 16; x += 512) {
;                     const bool isM = x < 512; const int y = isM ? x : x - 512; const int nf = isM ? 8 : 16; const int pos = y / nf, f = y % nf;
.LBB0_554:
	v_readlane_b32 s1, v254, 0
	s_nop 3
	s_sub_i32 s0, s62, s1
	s_add_i32 s0, s0, -1
	s_cmp_lt_u32 s0, 3
	s_cselect_b32 s0, s0, 0
	s_lshl_b32 s0, s0, 9
	v_add_u32_e32 v128, s0, v128
	s_movk_i32 s0, 0x600
	v_cmp_gt_i32_e32 vcc, s0, v128
	v_readlane_b32 s0, v252, 30
	v_readlane_b32 s1, v252, 31
	s_and_b64 s[0:1], s[0:1], vcc
	s_and_saveexec_b64 s[6:7], s[0:1]
	s_cbranch_execz .LBB0_563
	s_mov_b64 s[8:9], 0

; __device__ __forceinline__ void sincos_d(double a, float& c, float& s) {
;     const double twopi = 6.283185307179586476925;
;     const double k = __builtin_rint(a / twopi);
;     const double r = a - k * twopi;
;     const double r2 = r * r;
;     double cs = 1.0, sn = r, tc = 1.0, ts = r;
; #pragma unroll 1
;     for (int i = 1; i <= 14; ++i) { tc = -tc * r2 / (double)((2 * i - 1) * (2 * i)); ts = -ts * r2 / (double)((2 * i) * (2 * i + 1)); cs += tc; sn += ts; }
;     c = (float)cs; s = (float)sn;
; }
; __global__ void __launch_bounds__(512, 2) mk_fwd(Args args) {
;     ...
;                 for (int x = tid; x < 64 * 8 + 64 * 16; x += 512) {
;                     const bool isM = x < 512; const int y = isM ? x : x - 512; const int nf = isM ? 8 : 16; const int pos = y / nf, f = y % nf;
;                     const double base = isM ? 0.31622776601683794 : 0.5623413251903491;
;                     double inv = 1.0; for (int i = 0; i < f; ++i) inv *= base;
;                     const float ang = (float)pos * (float)inv;
;                     float c, s; sincos_d((double)ang, c, s);
;                     float* tp = isM ? tabM : tabS; tp[2 * y] = c; tp[2 * y + 1] = s;
;                 }
.LBB0_561:
	s_add_i32 s4, s2, -1
	s_mul_i32 s4, s4, s2
	v_cvt_f64_i32_e32 v[14:15], s4
	s_add_i32 s4, s4, s10
	v_mul_f64 v[12:13], v[6:7], -v[12:13]
	v_mul_f64 v[10:11], v[8:9], -v[10:11]
	v_cvt_f64_u32_e32 v[16:17], s4
	v_div_scale_f64 v[18:19], s[4:5], v[14:15], v[14:15], v[12:13]
	v_div_scale_f64 v[22:23], s[12:13], v[16:17], v[16:17], v[10:11]
	v_rcp_f64_e32 v[26:27], v[18:19]
	v_rcp_f64_e32 v[28:29], v[22:23]
	v_div_scale_f64 v[20:21], s[4:5], v[12:13], v[14:15], v[12:13]
	v_fma_f64 v[30:31], -v[18:19], v[26:27], 1.0
	v_fma_f64 v[32:33], -v[22:23], v[28:29], 1.0
	v_fmac_f64_e32 v[26:27], v[26:27], v[30:31]
	v_fmac_f64_e32 v[28:29], v[28:29], v[32:33]
	v_fma_f64 v[30:31], -v[18:19], v[26:27], 1.0
	v_fma_f64 v[32:33], -v[22:23], v[28:29], 1.0
	v_div_scale_f64 v[24:25], vcc, v[10:11], v[16:17], v[10:11]
	v_fmac_f64_e32 v[26:27], v[26:27], v[30:31]
	v_fmac_f64_e32 v[28:29], v[28:29], v[32:33]
	v_mul_f64 v[30:31], v[20:21], v[26:27]
	v_mul_f64 v[32:33], v[24:25], v[28:29]
	v_fma_f64 v[18:19], -v[18:19], v[30:31], v[20:21]
	v_fma_f64 v[20:21], -v[22:23], v[32:33], v[24:25]
	v_div_fmas_f64 v[20:21], v[20:21], v[28:29], v[32:33]
	s_mov_b64 vcc, s[4:5]
	v_div_fixup_f64 v[10:11], v[20:21], v[16:17], v[10:11]
	v_div_fmas_f64 v[16:17], v[18:19], v[26:27], v[30:31]
	s_add_i32 s2, s2, 2
	s_add_i32 s10, s10, 4
	v_div_fixup_f64 v[12:13], v[16:17], v[14:15], v[12:13]
	s_cmp_lg_u32 s2, 30
	v_add_f64 v[4:5], v[4:5], v[10:11]
	v_add_f64 v[2:3], v[2:3], v[12:13]
	s_cbranch_scc1 .LBB0_561
	v_cvt_f32_f64_e32 v5, v[4:5]
	v_cvt_f32_f64_e32 v4, v[2:3]
	v_mov_b32_e32 v2, s99
	v_mov_b32_e32 v3, s37
	v_cndmask_b32_e64 v3, v2, v3, s[0:1]
	v_mov_b32_e32 v2, s98
	v_mov_b32_e32 v6, s36
	v_cndmask_b32_e64 v2, v2, v6, s[0:1]
	v_lshlrev_b32_e32 v6, 1, v0
	v_ashrrev_i32_e32 v7, 31, v6
	v_add_u32_e32 v0, 0x200, v128
	v_cmp_lt_i32_e32 vcc, -1, v128
	v_lshl_add_u64 v[2:3], v[6:7], 2, v[2:3]
	s_or_b64 s[8:9], vcc, s[8:9]
	v_mov_b32_e32 v128, v0
	flat_store_dwordx2 v[2:3], v[4:5]
	s_andn2_b64 exec, exec, s[8:9]
	s_cbranch_execnz .LBB0_556
